# prologue fence v1 plus one early buffer_wbl2 per XCD slot (workgroups 0-7, wave 1) right after the opening barrier of each grid sync
# baseline (speedup 1.0000x reference)
; __device__ __forceinline__ void xcd_barrier(const XcdBarrier& b) {
;     asm volatile("s_waitcnt vmcnt(0)" ::: "memory");
;     __syncthreads();
.LBB0_204:
	s_waitcnt vmcnt(0)
	s_waitcnt vmcnt(0) lgkmcnt(0)
	s_barrier
	s_lshr_b32 s100, s2, 3
	s_cmp_eq_u32 s100, 0
	s_cbranch_scc0 .Lewb_lbb0_204
	v_readfirstlane_b32 s100, v202
	s_nop 3
	s_lshr_b32 s100, s100, 6
	s_cmp_eq_u32 s100, 1
	s_cbranch_scc0 .Lewb_lbb0_204
	buffer_wbl2 sc1

; __device__ __forceinline__ void xcd_barrier(const XcdBarrier& b) {
;     asm volatile("s_waitcnt vmcnt(0)" ::: "memory");
;     __syncthreads();
.LBB0_306:
	s_waitcnt vmcnt(0)
	s_barrier
	s_lshr_b32 s100, s2, 3
	s_cmp_eq_u32 s100, 0
	s_cbranch_scc0 .Lewb_lbb0_306
	v_readfirstlane_b32 s100, v202
	s_nop 3
	s_lshr_b32 s100, s100, 6
	s_cmp_eq_u32 s100, 1
	s_cbranch_scc0 .Lewb_lbb0_306
	buffer_wbl2 sc1

; __device__ __forceinline__ void xcd_barrier(const XcdBarrier& b) {
;     asm volatile("s_waitcnt vmcnt(0)" ::: "memory");
;     __syncthreads();
.LBB0_408:
	s_waitcnt vmcnt(0)
	s_waitcnt lgkmcnt(0)
	s_barrier
	s_lshr_b32 s100, s2, 3
	s_cmp_eq_u32 s100, 0
	s_cbranch_scc0 .Lewb_lbb0_408
	v_readfirstlane_b32 s100, v202
	s_nop 3
	s_lshr_b32 s100, s100, 6
	s_cmp_eq_u32 s100, 1
	s_cbranch_scc0 .Lewb_lbb0_408
	buffer_wbl2 sc1
